# k16 + first FFN-down residual epilogue (f32 x input) rewritten: x loads run 3 row groups ahead with counted vmcnt instead of a load+wait per row group, packed squares, permlane-swap reduction
# baseline (speedup 1.0000x reference)
; __device__ __forceinline__ unsigned cvtpk(float lo, float hi) { f32x2_t v = {lo, hi}; bf16x2_t b = __builtin_convertvector(v, bf16x2_t); return __builtin_bit_cast(unsigned, b); }
; __device__ __forceinline__ float bflo(unsigned w) { return __uint_as_float(w << 16); }
; __device__ __forceinline__ float bfhi(unsigned w) { return __uint_as_float(w & 0xffff0000u); }
;     __device__ __forceinline__ void operator()(const f32x4 (&acc)[2][2][4][2], const Unit& u, int wr, int wc, int fr, int fq) const {
;     ...
;         for (int ai = 0; ai < 2; ++ai)
; #pragma unroll
;             for (int m = 0; m < 4; ++m) {
;                 const int row = row0 + ai * HALF + m * 16; float s = 0.f;
; #pragma unroll
;                 for (int bj = 0; bj < 2; ++bj) {
;                     const size_t off = (size_t)row * DM + col0 + bj * HALF;
;                     f32x4 v0, v1;
;                     if (RM == 0) { v0 = *(const f32x4*)(xf + off); v1 = *(const f32x4*)(xf + off + 4); }
;                     else { const u32x4 w = xv[RM == 0 ? 0 : ai][RM == 0 ? 0 : m][RM == 0 ? 0 : bj]; v0 = (f32x4){bflo(w.x), bfhi(w.x), bflo(w.y), bfhi(w.y)}; v1 = (f32x4){bflo(w.z), bfhi(w.z), bflo(w.w), bfhi(w.w)}; }
;                     v0 = v0 + acc[ai][bj][m][0] * alpha; v1 = v1 + acc[ai][bj][m][1] * alpha;
;                     if (RM == 2) { *(f32x4*)(outf + off) = v0; *(f32x4*)(outf + off + 4) = v1; }
;                     else {
;                         u32x4 w; w.x = cvtpk(v0[0], v0[1]); w.y = cvtpk(v0[2], v0[3]); w.z = cvtpk(v1[0], v1[1]); w.w = cvtpk(v1[2], v1[3]);
;                         *(u32x4*)(xb + off) = w;
;                         s += (v0[0] * v0[0] + v0[1] * v0[1]) + (v0[2] * v0[2] + v0[3] * v0[3]) + (v1[0] * v1[0] + v1[1] * v1[1]) + (v1[2] * v1[2] + v1[3] * v1[3]);
;                     }
;                 }
;                 if (RM != 2) { s += __shfl_xor(s, 16); s += __shfl_xor(s, 32); if (fq == 0) ssq_out[(size_t)row * 16 + u.pn * 4 + wc] = s; }
.LBB0_373:
	v_lshl_or_b32 v144, s20, 8, v151
	v_lshl_add_u32 v145, s58, 8, v149
	v_lshl_add_u32 v213, v145, 10, v144
	v_lshlrev_b32_e32 v212, 2, v213
	v_lshlrev_b32_e32 v213, 1, v213
	global_load_dwordx4 v[156:159], v212, s[16:17]
	global_load_dwordx4 v[160:163], v212, s[16:17] offset:16
	global_load_dwordx4 v[164:167], v212, s[16:17] offset:512
	global_load_dwordx4 v[168:171], v212, s[16:17] offset:528
	v_add_u32_e32 v214, 0x10000, v212
	global_load_dwordx4 v[172:175], v214, s[16:17]
	global_load_dwordx4 v[176:179], v214, s[16:17] offset:16
	global_load_dwordx4 v[180:183], v214, s[16:17] offset:512
	global_load_dwordx4 v[184:187], v214, s[16:17] offset:528
	v_add_u32_e32 v214, 0x20000, v212
	global_load_dwordx4 v[188:191], v214, s[16:17]
	global_load_dwordx4 v[192:195], v214, s[16:17] offset:16
	global_load_dwordx4 v[196:199], v214, s[16:17] offset:512
	global_load_dwordx4 v[200:203], v214, s[16:17] offset:528
	s_waitcnt vmcnt(8)
	v_pk_fma_f32 v[124:125], v[124:125], 0.5, v[156:157] op_sel_hi:[1,0,1]
	v_pk_fma_f32 v[126:127], v[126:127], 0.5, v[158:159] op_sel_hi:[1,0,1]
	v_pk_fma_f32 v[120:121], v[120:121], 0.5, v[160:161] op_sel_hi:[1,0,1]
	v_pk_fma_f32 v[122:123], v[122:123], 0.5, v[162:163] op_sel_hi:[1,0,1]
	v_cvt_pk_bf16_f32 v156, v124, v125
	v_cvt_pk_bf16_f32 v157, v126, v127
	v_cvt_pk_bf16_f32 v158, v120, v121
	v_cvt_pk_bf16_f32 v159, v122, v123
	global_store_dwordx4 v213, v[156:159], s[24:25]
	v_pk_mul_f32 v[144:145], v[124:125], v[124:125]
	v_pk_fma_f32 v[144:145], v[126:127], v[126:127], v[144:145]
	v_pk_fma_f32 v[144:145], v[120:121], v[120:121], v[144:145]
	v_pk_fma_f32 v[144:145], v[122:123], v[122:123], v[144:145]
	v_pk_fma_f32 v[116:117], v[116:117], 0.5, v[164:165] op_sel_hi:[1,0,1]
	v_pk_fma_f32 v[118:119], v[118:119], 0.5, v[166:167] op_sel_hi:[1,0,1]
	v_pk_fma_f32 v[112:113], v[112:113], 0.5, v[168:169] op_sel_hi:[1,0,1]
	v_pk_fma_f32 v[114:115], v[114:115], 0.5, v[170:171] op_sel_hi:[1,0,1]
	v_cvt_pk_bf16_f32 v164, v116, v117
	v_cvt_pk_bf16_f32 v165, v118, v119
	v_cvt_pk_bf16_f32 v166, v112, v113
	v_cvt_pk_bf16_f32 v167, v114, v115
	global_store_dwordx4 v213, v[164:167], s[24:25] offset:256
	v_pk_mul_f32 v[146:147], v[116:117], v[116:117]
	v_pk_fma_f32 v[146:147], v[118:119], v[118:119], v[146:147]
	v_pk_fma_f32 v[146:147], v[112:113], v[112:113], v[146:147]
	v_pk_fma_f32 v[146:147], v[114:115], v[114:115], v[146:147]
	v_pk_add_f32 v[144:145], v[144:145], v[146:147]
	v_add_f32_e32 v204, v144, v145
	v_add_u32_e32 v214, 0x30000, v212
	global_load_dwordx4 v[124:127], v214, s[16:17]
	global_load_dwordx4 v[120:123], v214, s[16:17] offset:16
	global_load_dwordx4 v[116:119], v214, s[16:17] offset:512
	global_load_dwordx4 v[112:115], v214, s[16:17] offset:528
	s_waitcnt vmcnt(10)
	v_pk_fma_f32 v[108:109], v[108:109], 0.5, v[172:173] op_sel_hi:[1,0,1]
	v_pk_fma_f32 v[110:111], v[110:111], 0.5, v[174:175] op_sel_hi:[1,0,1]
	v_pk_fma_f32 v[104:105], v[104:105], 0.5, v[176:177] op_sel_hi:[1,0,1]
	v_pk_fma_f32 v[106:107], v[106:107], 0.5, v[178:179] op_sel_hi:[1,0,1]
	v_cvt_pk_bf16_f32 v172, v108, v109
	v_cvt_pk_bf16_f32 v173, v110, v111
	v_cvt_pk_bf16_f32 v174, v104, v105
	v_cvt_pk_bf16_f32 v175, v106, v107
	v_add_u32_e32 v215, 0x8000, v213
	global_store_dwordx4 v215, v[172:175], s[24:25]
	v_pk_mul_f32 v[144:145], v[108:109], v[108:109]
	v_pk_fma_f32 v[144:145], v[110:111], v[110:111], v[144:145]
	v_pk_fma_f32 v[144:145], v[104:105], v[104:105], v[144:145]
	v_pk_fma_f32 v[144:145], v[106:107], v[106:107], v[144:145]
	v_pk_fma_f32 v[100:101], v[100:101], 0.5, v[180:181] op_sel_hi:[1,0,1]
	v_pk_fma_f32 v[102:103], v[102:103], 0.5, v[182:183] op_sel_hi:[1,0,1]
	v_pk_fma_f32 v[96:97], v[96:97], 0.5, v[184:185] op_sel_hi:[1,0,1]
	v_pk_fma_f32 v[98:99], v[98:99], 0.5, v[186:187] op_sel_hi:[1,0,1]
	v_cvt_pk_bf16_f32 v180, v100, v101
	v_cvt_pk_bf16_f32 v181, v102, v103
	v_cvt_pk_bf16_f32 v182, v96, v97
	v_cvt_pk_bf16_f32 v183, v98, v99
	global_store_dwordx4 v215, v[180:183], s[24:25] offset:256
	v_pk_mul_f32 v[146:147], v[100:101], v[100:101]
	v_pk_fma_f32 v[146:147], v[102:103], v[102:103], v[146:147]
	v_pk_fma_f32 v[146:147], v[96:97], v[96:97], v[146:147]
	v_pk_fma_f32 v[146:147], v[98:99], v[98:99], v[146:147]
	v_pk_add_f32 v[144:145], v[144:145], v[146:147]
	v_add_f32_e32 v205, v144, v145
	v_add_u32_e32 v214, 0x80000, v212
	global_load_dwordx4 v[108:111], v214, s[16:17]
	global_load_dwordx4 v[104:107], v214, s[16:17] offset:16
	global_load_dwordx4 v[100:103], v214, s[16:17] offset:512
	global_load_dwordx4 v[96:99], v214, s[16:17] offset:528
	s_waitcnt vmcnt(12)
	v_pk_fma_f32 v[92:93], v[92:93], 0.5, v[188:189] op_sel_hi:[1,0,1]
	v_pk_fma_f32 v[94:95], v[94:95], 0.5, v[190:191] op_sel_hi:[1,0,1]
	v_pk_fma_f32 v[88:89], v[88:89], 0.5, v[192:193] op_sel_hi:[1,0,1]
	v_pk_fma_f32 v[90:91], v[90:91], 0.5, v[194:195] op_sel_hi:[1,0,1]
	v_cvt_pk_bf16_f32 v188, v92, v93
	v_cvt_pk_bf16_f32 v189, v94, v95
	v_cvt_pk_bf16_f32 v190, v88, v89
	v_cvt_pk_bf16_f32 v191, v90, v91
	v_add_u32_e32 v215, 0x10000, v213
	global_store_dwordx4 v215, v[188:191], s[24:25]
	v_pk_mul_f32 v[144:145], v[92:93], v[92:93]
	v_pk_fma_f32 v[144:145], v[94:95], v[94:95], v[144:145]
	v_pk_fma_f32 v[144:145], v[88:89], v[88:89], v[144:145]
	v_pk_fma_f32 v[144:145], v[90:91], v[90:91], v[144:145]
	v_pk_fma_f32 v[84:85], v[84:85], 0.5, v[196:197] op_sel_hi:[1,0,1]
	v_pk_fma_f32 v[86:87], v[86:87], 0.5, v[198:199] op_sel_hi:[1,0,1]
	v_pk_fma_f32 v[80:81], v[80:81], 0.5, v[200:201] op_sel_hi:[1,0,1]
	v_pk_fma_f32 v[82:83], v[82:83], 0.5, v[202:203] op_sel_hi:[1,0,1]
	v_cvt_pk_bf16_f32 v196, v84, v85
	v_cvt_pk_bf16_f32 v197, v86, v87
	v_cvt_pk_bf16_f32 v198, v80, v81
	v_cvt_pk_bf16_f32 v199, v82, v83
	global_store_dwordx4 v215, v[196:199], s[24:25] offset:256
	v_pk_mul_f32 v[146:147], v[84:85], v[84:85]
	v_pk_fma_f32 v[146:147], v[86:87], v[86:87], v[146:147]
	v_pk_fma_f32 v[146:147], v[80:81], v[80:81], v[146:147]
	v_pk_fma_f32 v[146:147], v[82:83], v[82:83], v[146:147]
	v_pk_add_f32 v[144:145], v[144:145], v[146:147]
	v_add_f32_e32 v206, v144, v145
	v_add_u32_e32 v214, 0x90000, v212
	global_load_dwordx4 v[92:95], v214, s[16:17]
	global_load_dwordx4 v[88:91], v214, s[16:17] offset:16
	global_load_dwordx4 v[84:87], v214, s[16:17] offset:512
	global_load_dwordx4 v[80:83], v214, s[16:17] offset:528
	s_waitcnt vmcnt(12)
; __device__ __forceinline__ unsigned cvtpk(float lo, float hi) { f32x2_t v = {lo, hi}; bf16x2_t b = __builtin_convertvector(v, bf16x2_t); return __builtin_bit_cast(unsigned, b); }
; __device__ __forceinline__ float bflo(unsigned w) { return __uint_as_float(w << 16); }
; __device__ __forceinline__ float bfhi(unsigned w) { return __uint_as_float(w & 0xffff0000u); }
;     __device__ __forceinline__ void operator()(const f32x4 (&acc)[2][2][4][2], const Unit& u, int wr, int wc, int fr, int fq) const {
;     ...
;         for (int ai = 0; ai < 2; ++ai)
; #pragma unroll
;             for (int m = 0; m < 4; ++m) {
;                 const int row = row0 + ai * HALF + m * 16; float s = 0.f;
; #pragma unroll
;                 for (int bj = 0; bj < 2; ++bj) {
;                     const size_t off = (size_t)row * DM + col0 + bj * HALF;
;                     f32x4 v0, v1;
;                     if (RM == 0) { v0 = *(const f32x4*)(xf + off); v1 = *(const f32x4*)(xf + off + 4); }
;                     else { const u32x4 w = xv[RM == 0 ? 0 : ai][RM == 0 ? 0 : m][RM == 0 ? 0 : bj]; v0 = (f32x4){bflo(w.x), bfhi(w.x), bflo(w.y), bfhi(w.y)}; v1 = (f32x4){bflo(w.z), bfhi(w.z), bflo(w.w), bfhi(w.w)}; }
;                     v0 = v0 + acc[ai][bj][m][0] * alpha; v1 = v1 + acc[ai][bj][m][1] * alpha;
;                     if (RM == 2) { *(f32x4*)(outf + off) = v0; *(f32x4*)(outf + off + 4) = v1; }
;                     else {
;                         u32x4 w; w.x = cvtpk(v0[0], v0[1]); w.y = cvtpk(v0[2], v0[3]); w.z = cvtpk(v1[0], v1[1]); w.w = cvtpk(v1[2], v1[3]);
;                         *(u32x4*)(xb + off) = w;
;                         s += (v0[0] * v0[0] + v0[1] * v0[1]) + (v0[2] * v0[2] + v0[3] * v0[3]) + (v1[0] * v1[0] + v1[1] * v1[1]) + (v1[2] * v1[2] + v1[3] * v1[3]);
;                     }
;                 }
	v_pk_fma_f32 v[76:77], v[76:77], 0.5, v[124:125] op_sel_hi:[1,0,1]
	v_pk_fma_f32 v[78:79], v[78:79], 0.5, v[126:127] op_sel_hi:[1,0,1]
	v_pk_fma_f32 v[72:73], v[72:73], 0.5, v[120:121] op_sel_hi:[1,0,1]
	v_pk_fma_f32 v[74:75], v[74:75], 0.5, v[122:123] op_sel_hi:[1,0,1]
	v_cvt_pk_bf16_f32 v124, v76, v77
	v_cvt_pk_bf16_f32 v125, v78, v79
	v_cvt_pk_bf16_f32 v126, v72, v73
	v_cvt_pk_bf16_f32 v127, v74, v75
	v_add_u32_e32 v215, 0x18000, v213
	global_store_dwordx4 v215, v[124:127], s[24:25]
	v_pk_mul_f32 v[144:145], v[76:77], v[76:77]
	v_pk_fma_f32 v[144:145], v[78:79], v[78:79], v[144:145]
	v_pk_fma_f32 v[144:145], v[72:73], v[72:73], v[144:145]
	v_pk_fma_f32 v[144:145], v[74:75], v[74:75], v[144:145]
	v_pk_fma_f32 v[68:69], v[68:69], 0.5, v[116:117] op_sel_hi:[1,0,1]
	v_pk_fma_f32 v[70:71], v[70:71], 0.5, v[118:119] op_sel_hi:[1,0,1]
	v_pk_fma_f32 v[64:65], v[64:65], 0.5, v[112:113] op_sel_hi:[1,0,1]
	v_pk_fma_f32 v[66:67], v[66:67], 0.5, v[114:115] op_sel_hi:[1,0,1]
	v_cvt_pk_bf16_f32 v116, v68, v69
	v_cvt_pk_bf16_f32 v117, v70, v71
	v_cvt_pk_bf16_f32 v118, v64, v65
	v_cvt_pk_bf16_f32 v119, v66, v67
	global_store_dwordx4 v215, v[116:119], s[24:25] offset:256
	v_pk_mul_f32 v[146:147], v[68:69], v[68:69]
	v_pk_fma_f32 v[146:147], v[70:71], v[70:71], v[146:147]
	v_pk_fma_f32 v[146:147], v[64:65], v[64:65], v[146:147]
	v_pk_fma_f32 v[146:147], v[66:67], v[66:67], v[146:147]
	v_pk_add_f32 v[144:145], v[144:145], v[146:147]
	v_add_f32_e32 v207, v144, v145
	v_add_u32_e32 v214, 0xa0000, v212
	global_load_dwordx4 v[76:79], v214, s[16:17]
	global_load_dwordx4 v[72:75], v214, s[16:17] offset:16
	global_load_dwordx4 v[68:71], v214, s[16:17] offset:512
	global_load_dwordx4 v[64:67], v214, s[16:17] offset:528
	s_waitcnt vmcnt(12)
	v_pk_fma_f32 v[60:61], v[60:61], 0.5, v[108:109] op_sel_hi:[1,0,1]
	v_pk_fma_f32 v[62:63], v[62:63], 0.5, v[110:111] op_sel_hi:[1,0,1]
	v_pk_fma_f32 v[56:57], v[56:57], 0.5, v[104:105] op_sel_hi:[1,0,1]
	v_pk_fma_f32 v[58:59], v[58:59], 0.5, v[106:107] op_sel_hi:[1,0,1]
	v_cvt_pk_bf16_f32 v108, v60, v61
	v_cvt_pk_bf16_f32 v109, v62, v63
	v_cvt_pk_bf16_f32 v110, v56, v57
	v_cvt_pk_bf16_f32 v111, v58, v59
	v_add_u32_e32 v215, 0x40000, v213
	global_store_dwordx4 v215, v[108:111], s[24:25]
	v_pk_mul_f32 v[144:145], v[60:61], v[60:61]
	v_pk_fma_f32 v[144:145], v[62:63], v[62:63], v[144:145]
	v_pk_fma_f32 v[144:145], v[56:57], v[56:57], v[144:145]
	v_pk_fma_f32 v[144:145], v[58:59], v[58:59], v[144:145]
	v_pk_fma_f32 v[52:53], v[52:53], 0.5, v[100:101] op_sel_hi:[1,0,1]
	v_pk_fma_f32 v[54:55], v[54:55], 0.5, v[102:103] op_sel_hi:[1,0,1]
	v_pk_fma_f32 v[48:49], v[48:49], 0.5, v[96:97] op_sel_hi:[1,0,1]
	v_pk_fma_f32 v[50:51], v[50:51], 0.5, v[98:99] op_sel_hi:[1,0,1]
	v_cvt_pk_bf16_f32 v100, v52, v53
	v_cvt_pk_bf16_f32 v101, v54, v55
	v_cvt_pk_bf16_f32 v102, v48, v49
	v_cvt_pk_bf16_f32 v103, v50, v51
	global_store_dwordx4 v215, v[100:103], s[24:25] offset:256
	v_pk_mul_f32 v[146:147], v[52:53], v[52:53]
	v_pk_fma_f32 v[146:147], v[54:55], v[54:55], v[146:147]
	v_pk_fma_f32 v[146:147], v[48:49], v[48:49], v[146:147]
	v_pk_fma_f32 v[146:147], v[50:51], v[50:51], v[146:147]
	v_pk_add_f32 v[144:145], v[144:145], v[146:147]
	v_add_f32_e32 v208, v144, v145
	v_add_u32_e32 v214, 0xb0000, v212
	global_load_dwordx4 v[60:63], v214, s[16:17]
	global_load_dwordx4 v[56:59], v214, s[16:17] offset:16
	global_load_dwordx4 v[52:55], v214, s[16:17] offset:512
	global_load_dwordx4 v[48:51], v214, s[16:17] offset:528
	s_waitcnt vmcnt(12)
	v_pk_fma_f32 v[44:45], v[44:45], 0.5, v[92:93] op_sel_hi:[1,0,1]
	v_pk_fma_f32 v[46:47], v[46:47], 0.5, v[94:95] op_sel_hi:[1,0,1]
	v_pk_fma_f32 v[40:41], v[40:41], 0.5, v[88:89] op_sel_hi:[1,0,1]
	v_pk_fma_f32 v[42:43], v[42:43], 0.5, v[90:91] op_sel_hi:[1,0,1]
	v_cvt_pk_bf16_f32 v92, v44, v45
	v_cvt_pk_bf16_f32 v93, v46, v47
	v_cvt_pk_bf16_f32 v94, v40, v41
	v_cvt_pk_bf16_f32 v95, v42, v43
	v_add_u32_e32 v215, 0x48000, v213
	global_store_dwordx4 v215, v[92:95], s[24:25]
	v_pk_mul_f32 v[144:145], v[44:45], v[44:45]
	v_pk_fma_f32 v[144:145], v[46:47], v[46:47], v[144:145]
	v_pk_fma_f32 v[144:145], v[40:41], v[40:41], v[144:145]
	v_pk_fma_f32 v[144:145], v[42:43], v[42:43], v[144:145]
	v_pk_fma_f32 v[36:37], v[36:37], 0.5, v[84:85] op_sel_hi:[1,0,1]
	v_pk_fma_f32 v[38:39], v[38:39], 0.5, v[86:87] op_sel_hi:[1,0,1]
	v_pk_fma_f32 v[32:33], v[32:33], 0.5, v[80:81] op_sel_hi:[1,0,1]
	v_pk_fma_f32 v[34:35], v[34:35], 0.5, v[82:83] op_sel_hi:[1,0,1]
	v_cvt_pk_bf16_f32 v84, v36, v37
	v_cvt_pk_bf16_f32 v85, v38, v39
	v_cvt_pk_bf16_f32 v86, v32, v33
	v_cvt_pk_bf16_f32 v87, v34, v35
	global_store_dwordx4 v215, v[84:87], s[24:25] offset:256
	v_pk_mul_f32 v[146:147], v[36:37], v[36:37]
	v_pk_fma_f32 v[146:147], v[38:39], v[38:39], v[146:147]
	v_pk_fma_f32 v[146:147], v[32:33], v[32:33], v[146:147]
	v_pk_fma_f32 v[146:147], v[34:35], v[34:35], v[146:147]
	v_pk_add_f32 v[144:145], v[144:145], v[146:147]
	v_add_f32_e32 v209, v144, v145
	s_waitcnt vmcnt(8)
; __device__ __forceinline__ float bflo(unsigned w) { return __uint_as_float(w << 16); }
; #define PG8_BAR __builtin_amdgcn_s_barrier()
; template <class Epi>
; __device__ __forceinline__ void gemm_phase(LAS unsigned char* lds, const Gemm g, const StaticOrder& S, const Epi& E, int wave_s) {
;     ...
;         if (wr == 0) PG8_BAR;
;         E(acc, cur, wr, wc, fr, fq);
;         if (!has_next) break;
; #pragma unroll
;         for (int a = 0; a < 2; ++a)
; #pragma unroll
;             for (int b = 0; b < 2; ++b)
; #pragma unroll
;                 for (int m = 0; m < 4; ++m)
; #pragma unroll
;                     for (int n = 0; n < 2; ++n) acc[a][b][m][n] = (f32x4){0.f, 0.f, 0.f, 0.f};
;         cur = nxt; cA = nA; cB = nB; ++ui;
;         if (wr == 1) PG8_BAR;
;     __device__ __forceinline__ void operator()(const f32x4 (&acc)[2][2][4][2], const Unit& u, int wr, int wc, int fr, int fq) const {
;     ...
;         for (int ai = 0; ai < 2; ++ai)
; #pragma unroll
;             for (int m = 0; m < 4; ++m) {
;                 const int row = row0 + ai * HALF + m * 16; float s = 0.f;
; #pragma unroll
;                 for (int bj = 0; bj < 2; ++bj) {
;                     const size_t off = (size_t)row * DM + col0 + bj * HALF;
;                     f32x4 v0, v1;
;                     if (RM == 0) { v0 = *(const f32x4*)(xf + off); v1 = *(const f32x4*)(xf + off + 4); }
;                     else { const u32x4 w = xv[RM == 0 ? 0 : ai][RM == 0 ? 0 : m][RM == 0 ? 0 : bj]; v0 = (f32x4){bflo(w.x), bfhi(w.x), bflo(w.y), bfhi(w.y)}; v1 = (f32x4){bflo(w.z), bfhi(w.z), bflo(w.w), bfhi(w.w)}; }
;                     v0 = v0 + acc[ai][bj][m][0] * alpha; v1 = v1 + acc[ai][bj][m][1] * alpha;
;                     if (RM == 2) { *(f32x4*)(outf + off) = v0; *(f32x4*)(outf + off + 4) = v1; }
;                     else {
;                         u32x4 w; w.x = cvtpk(v0[0], v0[1]); w.y = cvtpk(v0[2], v0[3]); w.z = cvtpk(v1[0], v1[1]); w.w = cvtpk(v1[2], v1[3]);
;                         *(u32x4*)(xb + off) = w;
;                         s += (v0[0] * v0[0] + v0[1] * v0[1]) + (v0[2] * v0[2] + v0[3] * v0[3]) + (v1[0] * v1[0] + v1[1] * v1[1]) + (v1[2] * v1[2] + v1[3] * v1[3]);
;                     }
;                 }
;                 if (RM != 2) { s += __shfl_xor(s, 16); s += __shfl_xor(s, 32); if (fq == 0) ssq_out[(size_t)row * 16 + u.pn * 4 + wc] = s; }
	v_pk_fma_f32 v[28:29], v[28:29], 0.5, v[76:77] op_sel_hi:[1,0,1]
	v_pk_fma_f32 v[30:31], v[30:31], 0.5, v[78:79] op_sel_hi:[1,0,1]
	v_pk_fma_f32 v[24:25], v[24:25], 0.5, v[72:73] op_sel_hi:[1,0,1]
	v_pk_fma_f32 v[26:27], v[26:27], 0.5, v[74:75] op_sel_hi:[1,0,1]
	v_cvt_pk_bf16_f32 v76, v28, v29
	v_cvt_pk_bf16_f32 v77, v30, v31
	v_cvt_pk_bf16_f32 v78, v24, v25
	v_cvt_pk_bf16_f32 v79, v26, v27
	v_add_u32_e32 v215, 0x50000, v213
	global_store_dwordx4 v215, v[76:79], s[24:25]
	v_pk_mul_f32 v[144:145], v[28:29], v[28:29]
	v_pk_fma_f32 v[144:145], v[30:31], v[30:31], v[144:145]
	v_pk_fma_f32 v[144:145], v[24:25], v[24:25], v[144:145]
	v_pk_fma_f32 v[144:145], v[26:27], v[26:27], v[144:145]
	v_pk_fma_f32 v[20:21], v[20:21], 0.5, v[68:69] op_sel_hi:[1,0,1]
	v_pk_fma_f32 v[22:23], v[22:23], 0.5, v[70:71] op_sel_hi:[1,0,1]
	v_pk_fma_f32 v[16:17], v[16:17], 0.5, v[64:65] op_sel_hi:[1,0,1]
	v_pk_fma_f32 v[18:19], v[18:19], 0.5, v[66:67] op_sel_hi:[1,0,1]
	v_cvt_pk_bf16_f32 v68, v20, v21
	v_cvt_pk_bf16_f32 v69, v22, v23
	v_cvt_pk_bf16_f32 v70, v16, v17
	v_cvt_pk_bf16_f32 v71, v18, v19
	global_store_dwordx4 v215, v[68:71], s[24:25] offset:256
	v_pk_mul_f32 v[146:147], v[20:21], v[20:21]
	v_pk_fma_f32 v[146:147], v[22:23], v[22:23], v[146:147]
	v_pk_fma_f32 v[146:147], v[16:17], v[16:17], v[146:147]
	v_pk_fma_f32 v[146:147], v[18:19], v[18:19], v[146:147]
	v_pk_add_f32 v[144:145], v[144:145], v[146:147]
	v_add_f32_e32 v210, v144, v145
	s_waitcnt vmcnt(4)
	v_pk_fma_f32 v[12:13], v[12:13], 0.5, v[60:61] op_sel_hi:[1,0,1]
	v_pk_fma_f32 v[14:15], v[14:15], 0.5, v[62:63] op_sel_hi:[1,0,1]
	v_pk_fma_f32 v[8:9], v[8:9], 0.5, v[56:57] op_sel_hi:[1,0,1]
	v_pk_fma_f32 v[10:11], v[10:11], 0.5, v[58:59] op_sel_hi:[1,0,1]
	v_cvt_pk_bf16_f32 v60, v12, v13
	v_cvt_pk_bf16_f32 v61, v14, v15
	v_cvt_pk_bf16_f32 v62, v8, v9
	v_cvt_pk_bf16_f32 v63, v10, v11
	v_add_u32_e32 v215, 0x58000, v213
	global_store_dwordx4 v215, v[60:63], s[24:25]
	v_pk_mul_f32 v[144:145], v[12:13], v[12:13]
	v_pk_fma_f32 v[144:145], v[14:15], v[14:15], v[144:145]
	v_pk_fma_f32 v[144:145], v[8:9], v[8:9], v[144:145]
	v_pk_fma_f32 v[144:145], v[10:11], v[10:11], v[144:145]
	v_pk_fma_f32 v[4:5], v[4:5], 0.5, v[52:53] op_sel_hi:[1,0,1]
	v_pk_fma_f32 v[6:7], v[6:7], 0.5, v[54:55] op_sel_hi:[1,0,1]
	v_pk_fma_f32 v[0:1], v[0:1], 0.5, v[48:49] op_sel_hi:[1,0,1]
	v_pk_fma_f32 v[2:3], v[2:3], 0.5, v[50:51] op_sel_hi:[1,0,1]
	v_cvt_pk_bf16_f32 v52, v4, v5
	v_cvt_pk_bf16_f32 v53, v6, v7
	v_cvt_pk_bf16_f32 v54, v0, v1
	v_cvt_pk_bf16_f32 v55, v2, v3
	global_store_dwordx4 v215, v[52:55], s[24:25] offset:256
	v_pk_mul_f32 v[146:147], v[4:5], v[4:5]
	v_pk_fma_f32 v[146:147], v[6:7], v[6:7], v[146:147]
	v_pk_fma_f32 v[146:147], v[0:1], v[0:1], v[146:147]
	v_pk_fma_f32 v[146:147], v[2:3], v[2:3], v[146:147]
	v_pk_add_f32 v[144:145], v[144:145], v[146:147]
	v_add_f32_e32 v211, v144, v145
	v_mbcnt_lo_u32_b32 v156, -1, 0
	v_mbcnt_hi_u32_b32 v156, -1, v156
	v_lshl_add_u32 v160, s58, 8, v149
	v_lshrrev_b32_e32 v157, 4, v156
	v_and_b32_e32 v158, 1, v157
	v_lshlrev_b32_e32 v158, 5, v158
	v_lshrrev_b32_e32 v157, 1, v157
	v_lshl_add_u32 v158, v157, 4, v158
	v_add_u32_e32 v158, v160, v158
	v_lshlrev_b32_e32 v158, 6, v158
	s_lshl_b32 s40, s20, 4
	s_lshl_b32 s41, s47, 2
	s_add_u32 s40, s40, s41
	v_add_u32_e32 v158, s40, v158
	v_add_u32_e32 v159, 0x2000, v158
	v_permlane32_swap_b32_e32 v204, v205
	v_permlane32_swap_b32_e32 v206, v207
	v_permlane32_swap_b32_e32 v208, v209
	v_permlane32_swap_b32_e32 v210, v211
	v_add_f32_e32 v204, v204, v205
	v_add_f32_e32 v206, v206, v207
	v_add_f32_e32 v208, v208, v209
	v_add_f32_e32 v210, v210, v211
	s_nop 1
	v_permlane16_swap_b32_e32 v204, v206
	v_permlane16_swap_b32_e32 v208, v210
	v_add_f32_e32 v204, v204, v206
	v_add_f32_e32 v208, v208, v210
	global_store_dword v158, v204, s[26:27]
	global_store_dword v159, v208, s[26:27]
	s_and_b64 vcc, exec, s[8:9]
	s_mov_b64 s[8:9], -1
	s_cbranch_vccnz .LBB0_358
	s_andn2_b64 vcc, exec, s[22:23]
	s_cbranch_vccnz .LBB0_357
	s_barrier
	s_branch .LBB0_357
